# attention loop: row-sum chain's trailing add of zero folded into the previous add
# speedup vs baseline: 1.0014x; 1.0014x over previous
;   #define RESC() do{ if(resc){ asm volatile("s_waitcnt lgkmcnt(0)":::"memory"); \
;       _Pragma("unroll") for(int d_=0;d_<2;++d_) _Pragma("unroll") for(int r=0;r<16;++r)o[d_][r]*=wsf[crow(r,hi)]; } }while(0)
;   #define ROT() do{sl_prev=sl_cur;sl_cur=sl_next;sl_next=(sl_next==(NSLOT-1)*SLOTB)?0:sl_next+SLOTB;}while(0)
;   #define WAIT_STEADY() WAIT_BAR(3)
;   #define WAIT_STEADY() WAIT_BAR(2)
; template<int THRL,bool NOMAX> __device__ __forceinline__ void attn_unit(int b,int h,int qb,int t0,const bf16*Q,const bf16*__restrict__ KV,const bf16*__restrict__ GA,bf16*O,char*shm){
;     ...
;   int t=1;
;     ...
;   for(;t+5<NT;t+=2){
;     STEP(pB0,pB1,pA0,pA1,t,true,true,true);     WAIT_STEADY(); RESC(); ROT();
;     STEP(pA0,pA1,pB0,pB1,t+1,true,true,true);   WAIT_STEADY(); RESC(); ROT();
;   }
.LBB0_479:
	v_add_u32_e32 v179, s16, v2
	ds_read_b64_tr_b16 v[198:199], v179 offset:24576
	ds_read_b64_tr_b16 v[200:201], v179 offset:25088
	v_add_f32_e32 v88, v68, v69
	v_add_f32_e32 v88, v70, v88
	v_add_f32_e32 v88, v71, v88
	v_add_f32_e32 v88, v72, v88
	v_add_f32_e32 v88, v73, v88
	v_cvt_pk_bf16_f32 v160, v68, v69
	v_cvt_pk_bf16_f32 v161, v70, v71
	v_mfma_f32_32x32x16_bf16 v[100:115], v[84:87], v[152:155], v[36:51]
	ds_read_b64_tr_b16 v[202:203], v179 offset:28672
	ds_read_b64_tr_b16 v[204:205], v179 offset:29184
	v_add_f32_e32 v68, v74, v88
	v_mfma_f32_32x32x16_bf16 v[84:99], v[168:171], v[152:155], v[36:51]
	v_add_f32_e32 v68, v75, v68
	v_add_f32_e32 v68, v76, v68
	v_add_f32_e32 v140, v77, v68
	v_cvt_pk_bf16_f32 v162, v72, v73
	v_cvt_pk_bf16_f32 v163, v74, v75
	ds_read_b64_tr_b16 v[68:69], v179 offset:25600
	ds_read_b64_tr_b16 v[70:71], v179 offset:26112
	v_add_f32_e32 v72, v78, v140
	v_add_f32_e32 v72, v79, v72
	v_add_f32_e32 v72, v80, v72
	v_add_f32_e32 v140, v81, v72
	v_cvt_pk_bf16_f32 v156, v76, v77
	v_cvt_pk_bf16_f32 v157, v78, v79
	v_mfma_f32_32x32x16_bf16 v[100:115], v[172:175], v[144:147], v[100:115]
	ds_read_b64_tr_b16 v[72:73], v179 offset:29696
	ds_read_b64_tr_b16 v[74:75], v179 offset:30208
	v_mfma_f32_32x32x16_bf16 v[84:99], v[164:167], v[144:147], v[84:99]
	v_add_f32_e32 v76, v82, v140
	v_add_f32_e32 v76, v83, v76
	v_add_f32_e32 v76, v52, v76
	v_add_f32_e32 v140, v53, v76
	v_cvt_pk_bf16_f32 v158, v80, v81
	v_cvt_pk_bf16_f32 v159, v82, v83
	ds_read_b64_tr_b16 v[76:77], v179 offset:26624
	ds_read_b64_tr_b16 v[78:79], v179 offset:27136
	v_add_f32_e32 v80, v54, v140
	v_add_f32_e32 v80, v55, v80
	v_add_f32_e32 v80, v56, v80
	v_add_f32_e32 v80, v57, v80
	v_cvt_pk_bf16_f32 v148, v52, v53
	v_cvt_pk_bf16_f32 v149, v54, v55
	v_mfma_f32_32x32x16_bf16 v[100:115], v[128:131], v[136:139], v[100:115]
	ds_read_b64_tr_b16 v[52:53], v179 offset:30720
	ds_read_b64_tr_b16 v[54:55], v179 offset:31232
	v_mfma_f32_32x32x16_bf16 v[84:99], v[124:127], v[136:139], v[84:99]
	v_add_f32_e32 v80, v58, v80
	v_add_f32_e32 v80, v59, v80
	v_add_f32_e32 v80, v60, v80
	v_add_f32_e32 v80, v61, v80
	v_cvt_pk_bf16_f32 v150, v56, v57
	v_cvt_pk_bf16_f32 v151, v58, v59
	ds_read_b64_tr_b16 v[56:57], v179 offset:27648
	ds_read_b64_tr_b16 v[58:59], v179 offset:28160
	v_add_f32_e32 v80, v62, v80
	v_add_f32_e32 v80, v63, v80
	v_add_f32_e32 v80, v64, v80
	v_add_f32_e32 v80, v65, v80
	v_cvt_pk_bf16_f32 v140, v60, v61
	v_cvt_pk_bf16_f32 v141, v62, v63
	v_mfma_f32_32x32x16_bf16 v[100:115], v[120:123], v[132:135], v[100:115]
	ds_read_b64_tr_b16 v[60:61], v179 offset:31744
	ds_read_b64_tr_b16 v[62:63], v179 offset:32256
	v_mfma_f32_32x32x16_bf16 v[84:99], v[116:119], v[132:135], v[84:99]
	v_add_f32_e32 v80, v66, v80
	v_add_f32_e32 v179, v67, v80
	v_cvt_pk_bf16_f32 v142, v64, v65
	v_cvt_pk_bf16_f32 v143, v66, v67
	s_add_i32 s16, s21, 0x4000
	s_and_b32 s16, s16, 0xfc000
	s_lshl_b32 s16, s16, 1
	v_lshl_add_u64 v[218:219], v[182:183], 0, s[16:17]
	s_add_i32 m0, s22, s9
	s_nop 0
	global_load_lds_dwordx4 v[218:219], off
	s_waitcnt lgkmcnt(4)
	v_mfma_f32_32x32x16_bf16 v[4:19], v[160:163], v[198:201], v[4:19]
	v_exp_f32_e32 v100, v100
	v_exp_f32_e32 v101, v101
	v_exp_f32_e32 v102, v102
	v_exp_f32_e32 v103, v103
	v_mfma_f32_32x32x16_bf16 v[20:35], v[160:163], v[202:205], v[20:35]
	v_exp_f32_e32 v104, v104
	v_exp_f32_e32 v105, v105
	v_exp_f32_e32 v106, v106
	v_exp_f32_e32 v107, v107
	v_add_u32_e32 v80, s15, v189
	ds_read_b128 v[64:67], v80
	ds_read_b128 v[120:123], v80 offset:512
	v_mfma_f32_32x32x16_bf16 v[4:19], v[156:159], v[68:71], v[4:19]
	v_exp_f32_e32 v108, v108
	v_exp_f32_e32 v109, v109
	v_exp_f32_e32 v110, v110
	v_exp_f32_e32 v111, v111
	ds_read_b128 v[124:127], v80 offset:2048
	ds_read_b128 v[128:131], v80 offset:2560
	v_mfma_f32_32x32x16_bf16 v[20:35], v[156:159], v[72:75], v[20:35]
	v_exp_f32_e32 v112, v112
	v_exp_f32_e32 v113, v113
	v_exp_f32_e32 v114, v114
	v_exp_f32_e32 v115, v115
	ds_read_b128 v[164:167], v80 offset:4096
	ds_read_b128 v[168:171], v80 offset:4608
	v_mfma_f32_32x32x16_bf16 v[4:19], v[148:151], v[76:79], v[4:19]
	v_exp_f32_e32 v84, v84
	v_exp_f32_e32 v85, v85
	v_exp_f32_e32 v86, v86
	v_exp_f32_e32 v87, v87
	ds_read_b128 v[172:175], v80 offset:6144
	ds_read_b128 v[116:119], v80 offset:6656
	v_mfma_f32_32x32x16_bf16 v[20:35], v[148:151], v[52:55], v[20:35]
	v_exp_f32_e32 v88, v88
	v_exp_f32_e32 v89, v89
	v_exp_f32_e32 v90, v90
	v_exp_f32_e32 v91, v91
	s_waitcnt lgkmcnt(8)
	v_mfma_f32_32x32x16_bf16 v[4:19], v[140:143], v[56:59], v[4:19]
	v_exp_f32_e32 v92, v92
	v_exp_f32_e32 v93, v93
	v_exp_f32_e32 v94, v94
	v_exp_f32_e32 v95, v95
	v_mfma_f32_32x32x16_bf16 v[20:35], v[140:143], v[60:63], v[20:35]
	v_exp_f32_e32 v96, v96
	v_exp_f32_e32 v97, v97
	v_exp_f32_e32 v98, v98
	v_exp_f32_e32 v99, v99
	s_add_i32 s16, s20, 0xffff4000
	s_and_b32 s16, s16, 0xfc000
	s_lshl_b32 s16, s16, 1
	v_lshl_add_u64 v[218:219], v[180:181], 0, s[16:17]
	s_add_i32 m0, s15, s8
	s_nop 0
	global_load_lds_dwordx4 v[218:219], off
	s_waitcnt vmcnt(2) lgkmcnt(0)
	s_barrier
;   #define RESC() do{ if(resc){ asm volatile("s_waitcnt lgkmcnt(0)":::"memory"); \
;       _Pragma("unroll") for(int d_=0;d_<2;++d_) _Pragma("unroll") for(int r=0;r<16;++r)o[d_][r]*=wsf[crow(r,hi)]; } }while(0)
;   #define ROT() do{sl_prev=sl_cur;sl_cur=sl_next;sl_next=(sl_next==(NSLOT-1)*SLOTB)?0:sl_next+SLOTB;}while(0)
;   #define WAIT_STEADY() WAIT_BAR(3)
;   #define WAIT_STEADY() WAIT_BAR(2)
; template<int THRL,bool NOMAX> __device__ __forceinline__ void attn_unit(int b,int h,int qb,int t0,const bf16*Q,const bf16*__restrict__ KV,const bf16*__restrict__ GA,bf16*O,char*shm){
;     ...
;   int t=1;
;     ...
;   for(;t+5<NT;t+=2){
;     STEP(pB0,pB1,pA0,pA1,t,true,true,true);     WAIT_STEADY(); RESC(); ROT();
;     STEP(pA0,pA1,pB0,pB1,t+1,true,true,true);   WAIT_STEADY(); RESC(); ROT();
;   }
	s_add_i32 s16, s15, 0x2000
	s_cmpk_lg_i32 s15, 0x4000
	s_cselect_b32 s23, s16, 0
	v_add_u32_e32 v190, s22, v2
	ds_read_b64_tr_b16 v[198:199], v190 offset:24576
	ds_read_b64_tr_b16 v[200:201], v190 offset:25088
	v_mfma_f32_32x32x16_bf16 v[68:83], v[64:67], v[152:155], v[36:51]
	v_add_f32_e32 v52, v100, v101
	v_add_f32_e32 v52, v102, v52
	v_add_f32_e32 v52, v103, v52
	v_add_f32_e32 v52, v104, v52
	v_add_f32_e32 v52, v105, v52
	v_cvt_pk_bf16_f32 v160, v100, v101
	v_cvt_pk_bf16_f32 v161, v102, v103
	ds_read_b64_tr_b16 v[202:203], v190 offset:28672
	ds_read_b64_tr_b16 v[204:205], v190 offset:29184
	v_add_f32_e32 v52, v106, v52
	v_add_f32_e32 v52, v107, v52
	v_add_f32_e32 v52, v108, v52
	v_add_f32_e32 v140, v109, v52
	v_mfma_f32_32x32x16_bf16 v[52:67], v[120:123], v[152:155], v[36:51]
	v_cvt_pk_bf16_f32 v162, v104, v105
	v_cvt_pk_bf16_f32 v163, v106, v107
	ds_read_b64_tr_b16 v[100:101], v190 offset:25600
	ds_read_b64_tr_b16 v[102:103], v190 offset:26112
	v_mfma_f32_32x32x16_bf16 v[68:83], v[124:127], v[144:147], v[68:83]
	v_add_f32_e32 v104, v110, v140
	v_add_f32_e32 v104, v111, v104
	v_add_f32_e32 v104, v112, v104
	v_add_f32_e32 v120, v113, v104
	v_cvt_pk_bf16_f32 v156, v108, v109
	v_cvt_pk_bf16_f32 v157, v110, v111
	ds_read_b64_tr_b16 v[104:105], v190 offset:29696
	ds_read_b64_tr_b16 v[106:107], v190 offset:30208
	v_mfma_f32_32x32x16_bf16 v[52:67], v[128:131], v[144:147], v[52:67]
	v_add_f32_e32 v108, v114, v120
	v_add_f32_e32 v108, v115, v108
	v_add_f32_e32 v108, v84, v108
	v_add_f32_e32 v120, v85, v108
	v_cvt_pk_bf16_f32 v158, v112, v113
	v_cvt_pk_bf16_f32 v159, v114, v115
	ds_read_b64_tr_b16 v[108:109], v190 offset:26624
	ds_read_b64_tr_b16 v[110:111], v190 offset:27136
	v_mfma_f32_32x32x16_bf16 v[68:83], v[164:167], v[136:139], v[68:83]
	v_add_f32_e32 v112, v86, v120
	v_add_f32_e32 v112, v87, v112
	v_add_f32_e32 v112, v88, v112
	v_add_f32_e32 v120, v89, v112
	v_cvt_pk_bf16_f32 v148, v84, v85
	v_cvt_pk_bf16_f32 v149, v86, v87
	ds_read_b64_tr_b16 v[112:113], v190 offset:30720
	ds_read_b64_tr_b16 v[114:115], v190 offset:31232
	v_mfma_f32_32x32x16_bf16 v[52:67], v[168:171], v[136:139], v[52:67]
	v_add_f32_e32 v84, v90, v120
	v_add_f32_e32 v84, v91, v84
	v_add_f32_e32 v84, v92, v84
	v_add_f32_e32 v84, v93, v84
	v_cvt_pk_bf16_f32 v150, v88, v89
	v_cvt_pk_bf16_f32 v151, v90, v91
	ds_read_b64_tr_b16 v[88:89], v190 offset:27648
	ds_read_b64_tr_b16 v[90:91], v190 offset:28160
	v_mfma_f32_32x32x16_bf16 v[68:83], v[172:175], v[132:135], v[68:83]
	v_add_f32_e32 v84, v94, v84
	v_add_f32_e32 v84, v95, v84
	v_add_f32_e32 v84, v96, v84
	v_add_f32_e32 v84, v97, v84
	v_cvt_pk_bf16_f32 v140, v92, v93
	v_cvt_pk_bf16_f32 v141, v94, v95
	ds_read_b64_tr_b16 v[92:93], v190 offset:31744
	ds_read_b64_tr_b16 v[94:95], v190 offset:32256
	v_mfma_f32_32x32x16_bf16 v[52:67], v[116:119], v[132:135], v[52:67]
	v_add_f32_e32 v84, v98, v84
	v_add_f32_e32 v190, v99, v84
	v_cvt_pk_bf16_f32 v142, v96, v97
	v_cvt_pk_bf16_f32 v143, v98, v99
	s_and_b32 s16, s20, 0xfc000
	s_lshl_b32 s16, s16, 1
	v_lshl_add_u64 v[218:219], v[182:183], 0, s[16:17]
	s_add_i32 m0, s15, s9
	s_nop 0
	global_load_lds_dwordx4 v[218:219], off
	s_waitcnt lgkmcnt(4)
	v_mfma_f32_32x32x16_bf16 v[4:19], v[160:163], v[198:201], v[4:19]
	v_exp_f32_e32 v68, v68
	v_exp_f32_e32 v69, v69
	v_exp_f32_e32 v70, v70
	v_exp_f32_e32 v71, v71
	v_mfma_f32_32x32x16_bf16 v[20:35], v[160:163], v[202:205], v[20:35]
	v_exp_f32_e32 v72, v72
	v_exp_f32_e32 v73, v73
	v_exp_f32_e32 v74, v74
	v_exp_f32_e32 v75, v75
	v_add_u32_e32 v96, s23, v189
	ds_read_b128 v[84:87], v96
	ds_read_b128 v[168:171], v96 offset:512
	v_mfma_f32_32x32x16_bf16 v[4:19], v[156:159], v[100:103], v[4:19]
	v_exp_f32_e32 v76, v76
	v_exp_f32_e32 v77, v77
	v_exp_f32_e32 v78, v78
	v_exp_f32_e32 v79, v79
	ds_read_b128 v[172:175], v96 offset:2048
	ds_read_b128 v[164:167], v96 offset:2560
	v_mfma_f32_32x32x16_bf16 v[20:35], v[156:159], v[104:107], v[20:35]
	v_exp_f32_e32 v80, v80
	v_exp_f32_e32 v81, v81
	v_exp_f32_e32 v82, v82
	v_exp_f32_e32 v83, v83
	ds_read_b128 v[128:131], v96 offset:4096
	ds_read_b128 v[124:127], v96 offset:4608
	v_mfma_f32_32x32x16_bf16 v[4:19], v[148:151], v[108:111], v[4:19]
	v_exp_f32_e32 v52, v52
	v_exp_f32_e32 v53, v53
	v_exp_f32_e32 v54, v54
	v_exp_f32_e32 v55, v55
	ds_read_b128 v[120:123], v96 offset:6144
	ds_read_b128 v[116:119], v96 offset:6656
	v_mfma_f32_32x32x16_bf16 v[20:35], v[148:151], v[112:115], v[20:35]
	v_exp_f32_e32 v56, v56
	v_exp_f32_e32 v57, v57
	v_exp_f32_e32 v58, v58
	v_exp_f32_e32 v59, v59
	s_waitcnt lgkmcnt(8)
	v_mfma_f32_32x32x16_bf16 v[4:19], v[140:143], v[88:91], v[4:19]
	v_exp_f32_e32 v60, v60
	v_exp_f32_e32 v61, v61
	v_exp_f32_e32 v62, v62
	v_exp_f32_e32 v63, v63
	v_mfma_f32_32x32x16_bf16 v[20:35], v[140:143], v[92:95], v[20:35]
	v_exp_f32_e32 v64, v64
	v_exp_f32_e32 v65, v65
	v_exp_f32_e32 v66, v66
	v_exp_f32_e32 v67, v67
	s_add_i32 s26, s23, 0x2000
	s_and_b32 s16, s21, 0xfc000
	s_lshl_b32 s16, s16, 1
	v_lshl_add_u64 v[218:219], v[180:181], 0, s[16:17]
	s_add_i32 m0, s23, s8
	s_nop 0
	global_load_lds_dwordx4 v[218:219], off
	s_waitcnt vmcnt(2) lgkmcnt(0)
	s_barrier
	s_cmpk_lg_i32 s23, 0x4000
	v_add_f32_e32 v88, v191, v179
	s_mov_b32 s16, s15
	s_cselect_b32 s15, s26, 0
	s_add_i32 s14, s14, 2
	s_add_i32 s21, s21, 0x8000
	s_add_i32 s20, s20, 0x8000
	s_mov_b32 s22, s23
	v_add_f32_e32 v191, v88, v190
	s_cmp_gt_u32 s14, 56
	s_cbranch_scc0 .LBB0_479
;   #define RESC() do{ if(resc){ asm volatile("s_waitcnt lgkmcnt(0)":::"memory"); \
;       _Pragma("unroll") for(int d_=0;d_<2;++d_) _Pragma("unroll") for(int r=0;r<16;++r)o[d_][r]*=wsf[crow(r,hi)]; } }while(0)
;   #define ROT() do{sl_prev=sl_cur;sl_cur=sl_next;sl_next=(sl_next==(NSLOT-1)*SLOTB)?0:sl_next+SLOTB;}while(0)
;   #define ENDW(tt) do{ if((tt)+3<NT){WAIT_BAR(2);} else if((tt)+2<NT){WAIT_BAR(1);} else {WAIT_BAR(0);} }while(0)
; template<int THRL,bool NOMAX> __device__ __forceinline__ void attn_unit(int b,int h,int qb,int t0,const bf16*Q,const bf16*__restrict__ KV,const bf16*__restrict__ GA,bf16*O,char*shm){
;     ...
;   for(;t+1<NT;t+=2){
;     STEP(pB0,pB1,pA0,pA1,t,(t+3<NT),(t+1<NT),(t+1<NT));       ENDW(t);   RESC(); ROT();
;     STEP(pA0,pA1,pB0,pB1,t+1,(t+4<NT),(t+2<NT),(t+2<NT));     ENDW(t+1); RESC(); ROT();
	s_and_b32 s12, s12, 0x3fffffc0
	s_cmp_lg_u32 0, -1
	s_cselect_b32 s14, 0, 0
	s_add_i32 s15, s14, 0x6000
	s_lshl_b32 s12, s12, 2
	v_add_u32_e32 v88, s15, v177
	s_add_i32 s12, s12, 0
	v_add3_u32 v190, v88, v176, v178
	ds_read_b64_tr_b16 v[198:199], v2 offset:32768
	ds_read_b64_tr_b16 v[200:201], v2 offset:33280
	v_add_f32_e32 v88, v68, v69
	v_add_f32_e32 v88, v70, v88
	v_add_f32_e32 v88, v71, v88
	v_add_f32_e32 v88, v72, v88
	v_add_f32_e32 v88, v73, v88
	v_cvt_pk_bf16_f32 v160, v68, v69
	v_cvt_pk_bf16_f32 v161, v70, v71
	s_waitcnt lgkmcnt(9)
	v_mfma_f32_32x32x16_bf16 v[100:115], v[84:87], v[152:155], v[36:51]
	ds_read_b64_tr_b16 v[176:177], v2 offset:36864
	ds_read_b64_tr_b16 v[178:179], v2 offset:37376
	v_add_f32_e32 v68, v74, v88
	v_add_f32_e32 v68, v75, v68
	v_add_f32_e32 v68, v76, v68
	v_add_f32_e32 v140, v77, v68
	v_cvt_pk_bf16_f32 v162, v72, v73
	v_cvt_pk_bf16_f32 v163, v74, v75
	s_waitcnt lgkmcnt(10)
	v_mfma_f32_32x32x16_bf16 v[84:99], v[168:171], v[152:155], v[36:51]
	ds_read_b64_tr_b16 v[68:69], v2 offset:33792
	ds_read_b64_tr_b16 v[70:71], v2 offset:34304
	v_add_f32_e32 v72, v78, v140
	v_add_f32_e32 v72, v79, v72
	v_add_f32_e32 v72, v80, v72
	v_add_f32_e32 v140, v81, v72
	v_cvt_pk_bf16_f32 v156, v76, v77
	v_cvt_pk_bf16_f32 v157, v78, v79
	s_waitcnt lgkmcnt(11)
	v_mfma_f32_32x32x16_bf16 v[100:115], v[172:175], v[144:147], v[100:115]
	ds_read_b64_tr_b16 v[72:73], v2 offset:37888
	ds_read_b64_tr_b16 v[74:75], v2 offset:38400
	v_add_f32_e32 v76, v82, v140
	v_add_f32_e32 v76, v83, v76
	v_add_f32_e32 v76, v52, v76
	v_add_f32_e32 v140, v53, v76
	v_cvt_pk_bf16_f32 v158, v80, v81
	v_cvt_pk_bf16_f32 v159, v82, v83
	s_waitcnt lgkmcnt(12)
	v_mfma_f32_32x32x16_bf16 v[84:99], v[164:167], v[144:147], v[84:99]
	ds_read_b64_tr_b16 v[76:77], v2 offset:34816
	ds_read_b64_tr_b16 v[78:79], v2 offset:35328
	v_add_f32_e32 v80, v54, v140
	v_add_f32_e32 v80, v55, v80
	v_add_f32_e32 v80, v56, v80
	v_add_f32_e32 v80, v57, v80
	v_cvt_pk_bf16_f32 v148, v52, v53
	v_cvt_pk_bf16_f32 v149, v54, v55
	s_waitcnt lgkmcnt(13)
	v_mfma_f32_32x32x16_bf16 v[100:115], v[128:131], v[136:139], v[100:115]
	ds_read_b64_tr_b16 v[52:53], v2 offset:38912
	ds_read_b64_tr_b16 v[54:55], v2 offset:39424
	v_add_f32_e32 v80, v58, v80
	v_add_f32_e32 v80, v59, v80
	v_add_f32_e32 v80, v60, v80
	v_add_f32_e32 v80, v61, v80
	v_cvt_pk_bf16_f32 v150, v56, v57
	v_cvt_pk_bf16_f32 v151, v58, v59
	s_waitcnt lgkmcnt(14)
	v_mfma_f32_32x32x16_bf16 v[84:99], v[124:127], v[136:139], v[84:99]
	ds_read_b64_tr_b16 v[56:57], v2 offset:35840
	ds_read_b64_tr_b16 v[58:59], v2 offset:36352
	v_add_f32_e32 v80, v62, v80
	v_add_f32_e32 v80, v63, v80
	v_add_f32_e32 v80, v64, v80
	v_add_f32_e32 v80, v65, v80
	v_cvt_pk_bf16_f32 v140, v60, v61
	v_cvt_pk_bf16_f32 v141, v62, v63
	s_waitcnt lgkmcnt(14)
	v_mfma_f32_32x32x16_bf16 v[100:115], v[120:123], v[132:135], v[100:115]
	ds_read_b64_tr_b16 v[60:61], v2 offset:39936
	ds_read_b64_tr_b16 v[62:63], v2 offset:40448
	v_add_f32_e32 v80, v66, v80
	v_add_f32_e32 v80, v67, v80
	v_add_f32_e32 v80, 0, v80
	v_cvt_pk_bf16_f32 v142, v64, v65
	v_cvt_pk_bf16_f32 v143, v66, v67
	v_mfma_f32_32x32x16_bf16 v[84:99], v[116:119], v[132:135], v[84:99]
	v_readlane_b32 s20, v254, 56
	v_readlane_b32 s21, v254, 57
	s_mov_b32 s21, s17
	s_add_i32 s13, s14, s13
	v_lshl_add_u64 v[64:65], v[182:183], 0, s[20:21]
	s_add_i32 s14, s13, 0x4000
	s_mov_b32 s15, m0
	s_mov_b32 m0, s14
	s_nop 0
	global_load_lds_dwordx4 v[64:65], off
	s_mov_b32 m0, s15
	v_add_f32_e32 v191, v191, v80
	v_readlane_b32 s14, v254, 58
	v_readlane_b32 s15, v254, 59
	s_mov_b32 s15, s17
	s_mov_b32 s16, s14
	v_lshl_add_u64 v[64:65], v[180:181], 0, s[14:15]
	s_mov_b32 s14, m0
	s_mov_b32 m0, s8
	s_nop 0
	global_load_lds_dwordx4 v[64:65], off
	s_mov_b32 m0, s14
	v_writelane_b32 v254, s16, 58
	s_nop 1
	v_writelane_b32 v254, s17, 59
	s_waitcnt lgkmcnt(14)
	v_mfma_f32_32x32x16_bf16 v[4:19], v[160:163], v[198:201], v[4:19]
	v_exp_f32_e32 v100, v100
	v_exp_f32_e32 v101, v101
	v_exp_f32_e32 v102, v102
	v_exp_f32_e32 v103, v103
	s_waitcnt lgkmcnt(12)
	v_mfma_f32_32x32x16_bf16 v[20:35], v[160:163], v[176:179], v[20:35]
	v_exp_f32_e32 v104, v104
	v_exp_f32_e32 v105, v105
	v_exp_f32_e32 v106, v106
	v_exp_f32_e32 v107, v107
	ds_read_b128 v[64:67], v189
	ds_read_b128 v[80:83], v189 offset:512
	s_waitcnt lgkmcnt(12)
	v_mfma_f32_32x32x16_bf16 v[4:19], v[156:159], v[68:71], v[4:19]
	v_exp_f32_e32 v108, v108
	v_exp_f32_e32 v109, v109
	v_exp_f32_e32 v110, v110
	v_exp_f32_e32 v111, v111
	ds_read_b128 v[164:167], v189 offset:2048
	ds_read_b128 v[168:171], v189 offset:2560
	s_waitcnt lgkmcnt(12)
	v_mfma_f32_32x32x16_bf16 v[20:35], v[156:159], v[72:75], v[20:35]
	v_exp_f32_e32 v112, v112
	v_exp_f32_e32 v113, v113
	v_exp_f32_e32 v114, v114
	v_exp_f32_e32 v115, v115
	ds_read_b128 v[172:175], v189 offset:4096
	ds_read_b128 v[176:179], v189 offset:4608
	s_waitcnt lgkmcnt(12)
	v_mfma_f32_32x32x16_bf16 v[4:19], v[148:151], v[76:79], v[4:19]
	v_exp_f32_e32 v84, v84
	v_exp_f32_e32 v85, v85
	v_exp_f32_e32 v86, v86
	v_exp_f32_e32 v87, v87
	ds_read_b128 v[198:201], v189 offset:6144
	ds_read_b128 v[72:75], v189 offset:6656
	s_waitcnt lgkmcnt(12)
	v_mfma_f32_32x32x16_bf16 v[20:35], v[148:151], v[52:55], v[20:35]
	v_exp_f32_e32 v88, v88
	v_exp_f32_e32 v89, v89
	v_exp_f32_e32 v90, v90
	v_exp_f32_e32 v91, v91
	s_waitcnt lgkmcnt(10)
	v_mfma_f32_32x32x16_bf16 v[4:19], v[140:143], v[56:59], v[4:19]
	v_exp_f32_e32 v92, v92
	v_exp_f32_e32 v93, v93
	v_exp_f32_e32 v94, v94
	v_exp_f32_e32 v95, v95
	s_waitcnt lgkmcnt(8)
	v_mfma_f32_32x32x16_bf16 v[20:35], v[140:143], v[60:63], v[20:35]
	v_exp_f32_e32 v96, v96
	v_exp_f32_e32 v97, v97
	v_exp_f32_e32 v98, v98
	v_exp_f32_e32 v99, v99
	s_waitcnt vmcnt(2) lgkmcnt(0)
	s_barrier
;   #define RESC() do{ if(resc){ asm volatile("s_waitcnt lgkmcnt(0)":::"memory"); \
;       _Pragma("unroll") for(int d_=0;d_<2;++d_) _Pragma("unroll") for(int r=0;r<16;++r)o[d_][r]*=wsf[crow(r,hi)]; } }while(0)
;   #define ROT() do{sl_prev=sl_cur;sl_cur=sl_next;sl_next=(sl_next==(NSLOT-1)*SLOTB)?0:sl_next+SLOTB;}while(0)
;   #define ENDW(tt) do{ if((tt)+3<NT){WAIT_BAR(2);} else if((tt)+2<NT){WAIT_BAR(1);} else {WAIT_BAR(0);} }while(0)
; template<int THRL,bool NOMAX> __device__ __forceinline__ void attn_unit(int b,int h,int qb,int t0,const bf16*Q,const bf16*__restrict__ KV,const bf16*__restrict__ GA,bf16*O,char*shm){
;     ...
;   for(;t+1<NT;t+=2){
;     STEP(pB0,pB1,pA0,pA1,t,(t+3<NT),(t+1<NT),(t+1<NT));       ENDW(t);   RESC(); ROT();
;     STEP(pA0,pA1,pB0,pB1,t+1,(t+4<NT),(t+2<NT),(t+2<NT));     ENDW(t+1); RESC(); ROT();
	ds_read_b64_tr_b16 v[202:203], v2 offset:40960
	ds_read_b64_tr_b16 v[204:205], v2 offset:41472
	v_add_f32_e32 v52, v100, v101
	v_add_f32_e32 v52, v102, v52
	v_add_f32_e32 v52, v103, v52
	v_add_f32_e32 v52, v104, v52
	v_add_f32_e32 v52, v105, v52
	v_cvt_pk_bf16_f32 v160, v100, v101
	v_cvt_pk_bf16_f32 v161, v102, v103
	s_waitcnt lgkmcnt(9)
	v_mfma_f32_32x32x16_bf16 v[116:131], v[64:67], v[152:155], v[36:51]
	ds_read_b64_tr_b16 v[100:101], v2 offset:45056
	ds_read_b64_tr_b16 v[102:103], v2 offset:45568
	v_add_f32_e32 v52, v106, v52
	v_add_f32_e32 v52, v107, v52
	v_add_f32_e32 v52, v108, v52
	v_add_f32_e32 v76, v109, v52
	v_cvt_pk_bf16_f32 v162, v104, v105
	v_cvt_pk_bf16_f32 v163, v106, v107
	s_waitcnt lgkmcnt(10)
	v_mfma_f32_32x32x16_bf16 v[52:67], v[80:83], v[152:155], v[36:51]
	ds_read_b64_tr_b16 v[68:69], v2 offset:41984
	ds_read_b64_tr_b16 v[70:71], v2 offset:42496
	v_add_f32_e32 v76, v110, v76
	v_add_f32_e32 v76, v111, v76
	v_add_f32_e32 v76, v112, v76
	v_add_f32_e32 v80, v113, v76
	v_cvt_pk_bf16_f32 v156, v108, v109
	v_cvt_pk_bf16_f32 v157, v110, v111
	s_waitcnt lgkmcnt(11)
	v_mfma_f32_32x32x16_bf16 v[116:131], v[164:167], v[144:147], v[116:131]
	ds_read_b64_tr_b16 v[76:77], v2 offset:46080
	ds_read_b64_tr_b16 v[78:79], v2 offset:46592
	v_add_f32_e32 v80, v114, v80
	v_add_f32_e32 v80, v115, v80
	v_add_f32_e32 v80, v84, v80
	v_add_f32_e32 v104, v85, v80
	v_cvt_pk_bf16_f32 v158, v112, v113
	v_cvt_pk_bf16_f32 v159, v114, v115
	s_waitcnt lgkmcnt(12)
	v_mfma_f32_32x32x16_bf16 v[52:67], v[168:171], v[144:147], v[52:67]
	ds_read_b64_tr_b16 v[80:81], v2 offset:43008
	ds_read_b64_tr_b16 v[82:83], v2 offset:43520
	v_add_f32_e32 v104, v86, v104
	v_add_f32_e32 v104, v87, v104
	v_add_f32_e32 v104, v88, v104
	v_add_f32_e32 v108, v89, v104
	v_cvt_pk_bf16_f32 v148, v84, v85
	v_cvt_pk_bf16_f32 v149, v86, v87
	s_waitcnt lgkmcnt(13)
	v_mfma_f32_32x32x16_bf16 v[116:131], v[172:175], v[136:139], v[116:131]
	ds_read_b64_tr_b16 v[104:105], v2 offset:47104
	ds_read_b64_tr_b16 v[106:107], v2 offset:47616
	v_add_f32_e32 v84, v90, v108
	v_add_f32_e32 v84, v91, v84
	v_add_f32_e32 v84, v92, v84
	v_add_f32_e32 v84, v93, v84
	v_cvt_pk_bf16_f32 v150, v88, v89
	v_cvt_pk_bf16_f32 v151, v90, v91
	s_waitcnt lgkmcnt(14)
	v_mfma_f32_32x32x16_bf16 v[52:67], v[176:179], v[136:139], v[52:67]
	ds_read_b64_tr_b16 v[88:89], v2 offset:44032
	ds_read_b64_tr_b16 v[90:91], v2 offset:44544
	v_add_f32_e32 v84, v94, v84
	v_add_f32_e32 v84, v95, v84
	v_add_f32_e32 v84, v96, v84
	v_add_f32_e32 v84, v97, v84
	v_cvt_pk_bf16_f32 v140, v92, v93
	v_cvt_pk_bf16_f32 v141, v94, v95
	s_waitcnt lgkmcnt(14)
	v_mfma_f32_32x32x16_bf16 v[116:131], v[198:201], v[132:135], v[116:131]
	ds_read_b64_tr_b16 v[92:93], v2 offset:48128
	ds_read_b64_tr_b16 v[94:95], v2 offset:48640
	v_mfma_f32_32x32x16_bf16 v[52:67], v[72:75], v[132:135], v[52:67]
	v_add_f32_e32 v72, v98, v84
	v_add_f32_e32 v72, v99, v72
	v_add_f32_e32 v72, 0, v72
	v_cvt_pk_bf16_f32 v142, v96, v97
	v_cvt_pk_bf16_f32 v143, v98, v99
	v_readlane_b32 s22, v254, 60
	v_readlane_b32 s23, v254, 61
	s_mov_b32 s23, s17
	v_add_f32_e32 v191, v191, v72
	v_lshl_add_u64 v[72:73], v[182:183], 0, s[22:23]
	s_mov_b32 s14, m0
	s_mov_b32 m0, s9
	s_nop 0
	global_load_lds_dwordx4 v[72:73], off
	s_mov_b32 m0, s14
	s_add_i32 s9, s13, 0x8000
	v_readlane_b32 s14, v254, 62
	v_readlane_b32 s15, v254, 63
	s_mov_b32 s15, s17
	s_mov_b32 s16, s14
	v_lshl_add_u64 v[72:73], v[180:181], 0, s[14:15]
	s_mov_b32 s14, m0
	s_mov_b32 m0, s9
	s_nop 0
	global_load_lds_dwordx4 v[72:73], off
	s_mov_b32 m0, s14
	v_writelane_b32 v254, s16, 62
	s_nop 1
	v_writelane_b32 v254, s17, 63
	s_waitcnt lgkmcnt(14)
	v_mfma_f32_32x32x16_bf16 v[4:19], v[160:163], v[202:205], v[4:19]
	v_exp_f32_e32 v116, v116
	v_exp_f32_e32 v117, v117
	v_exp_f32_e32 v118, v118
	v_exp_f32_e32 v119, v119
	s_waitcnt lgkmcnt(12)
	v_mfma_f32_32x32x16_bf16 v[20:35], v[160:163], v[100:103], v[20:35]
	v_exp_f32_e32 v120, v120
	v_exp_f32_e32 v121, v121
	v_exp_f32_e32 v122, v122
	v_exp_f32_e32 v123, v123
	ds_read_b128 v[72:75], v189 offset:8192
	ds_read_b128 v[96:99], v189 offset:8704
	s_waitcnt lgkmcnt(12)
	v_mfma_f32_32x32x16_bf16 v[4:19], v[156:159], v[68:71], v[4:19]
	v_exp_f32_e32 v124, v124
	v_exp_f32_e32 v125, v125
	v_exp_f32_e32 v126, v126
	v_exp_f32_e32 v127, v127
	ds_read_b128 v[164:167], v189 offset:10240
	ds_read_b128 v[168:171], v189 offset:10752
	s_waitcnt lgkmcnt(12)
	v_mfma_f32_32x32x16_bf16 v[20:35], v[156:159], v[76:79], v[20:35]
	v_exp_f32_e32 v128, v128
	v_exp_f32_e32 v129, v129
	v_exp_f32_e32 v130, v130
	v_exp_f32_e32 v131, v131
	ds_read_b128 v[172:175], v189 offset:12288
	ds_read_b128 v[176:179], v189 offset:12800
	s_waitcnt lgkmcnt(12)
	v_mfma_f32_32x32x16_bf16 v[4:19], v[148:151], v[80:83], v[4:19]
	v_exp_f32_e32 v52, v52
	v_exp_f32_e32 v53, v53
	v_exp_f32_e32 v54, v54
	v_exp_f32_e32 v55, v55
	ds_read_b128 v[198:201], v189 offset:14336
	ds_read_b128 v[84:87], v189 offset:14848
	s_waitcnt lgkmcnt(12)
	v_mfma_f32_32x32x16_bf16 v[20:35], v[148:151], v[104:107], v[20:35]
	v_exp_f32_e32 v56, v56
	v_exp_f32_e32 v57, v57
	v_exp_f32_e32 v58, v58
	v_exp_f32_e32 v59, v59
	s_waitcnt lgkmcnt(10)
	v_mfma_f32_32x32x16_bf16 v[4:19], v[140:143], v[88:91], v[4:19]
	v_exp_f32_e32 v60, v60
	v_exp_f32_e32 v61, v61
	v_exp_f32_e32 v62, v62
	v_exp_f32_e32 v63, v63
	s_waitcnt lgkmcnt(8)
	v_mfma_f32_32x32x16_bf16 v[20:35], v[140:143], v[92:95], v[20:35]
	v_exp_f32_e32 v64, v64
	v_exp_f32_e32 v65, v65
	v_exp_f32_e32 v66, v66
	v_exp_f32_e32 v67, v67
	s_waitcnt vmcnt(2) lgkmcnt(0)
	s_barrier
;   #define RESC() do{ if(resc){ asm volatile("s_waitcnt lgkmcnt(0)":::"memory"); \
;       _Pragma("unroll") for(int d_=0;d_<2;++d_) _Pragma("unroll") for(int r=0;r<16;++r)o[d_][r]*=wsf[crow(r,hi)]; } }while(0)
;   #define ROT() do{sl_prev=sl_cur;sl_cur=sl_next;sl_next=(sl_next==(NSLOT-1)*SLOTB)?0:sl_next+SLOTB;}while(0)
;   #define ENDW(tt) do{ if((tt)+3<NT){WAIT_BAR(2);} else if((tt)+2<NT){WAIT_BAR(1);} else {WAIT_BAR(0);} }while(0)
; template<int THRL,bool NOMAX> __device__ __forceinline__ void attn_unit(int b,int h,int qb,int t0,const bf16*Q,const bf16*__restrict__ KV,const bf16*__restrict__ GA,bf16*O,char*shm){
;     ...
;   for(;t+1<NT;t+=2){
;     STEP(pB0,pB1,pA0,pA1,t,(t+3<NT),(t+1<NT),(t+1<NT));       ENDW(t);   RESC(); ROT();
;     STEP(pA0,pA1,pB0,pB1,t+1,(t+4<NT),(t+2<NT),(t+2<NT));     ENDW(t+1); RESC(); ROT();
	ds_read_b64_tr_b16 v[88:89], v2 offset:24576
	ds_read_b64_tr_b16 v[90:91], v2 offset:25088
	v_add_f32_e32 v68, v116, v117
	v_add_f32_e32 v68, v118, v68
	v_add_f32_e32 v68, v119, v68
	v_add_f32_e32 v68, v120, v68
	v_add_f32_e32 v68, v121, v68
	v_cvt_pk_bf16_f32 v160, v116, v117
	v_cvt_pk_bf16_f32 v161, v118, v119
	s_waitcnt lgkmcnt(9)
	v_mfma_f32_32x32x16_bf16 v[100:115], v[72:75], v[152:155], v[36:51]
	ds_read_b64_tr_b16 v[92:93], v2 offset:28672
	ds_read_b64_tr_b16 v[94:95], v2 offset:29184
	v_add_f32_e32 v68, v122, v68
	v_add_f32_e32 v68, v123, v68
	v_add_f32_e32 v68, v124, v68
	v_add_f32_e32 v116, v125, v68
	v_cvt_pk_bf16_f32 v162, v120, v121
	v_cvt_pk_bf16_f32 v163, v122, v123
	s_waitcnt lgkmcnt(10)
	v_mfma_f32_32x32x16_bf16 v[68:83], v[96:99], v[152:155], v[36:51]
	ds_read_b64_tr_b16 v[96:97], v2 offset:25600
	ds_read_b64_tr_b16 v[98:99], v2 offset:26112
	v_add_f32_e32 v116, v126, v116
	v_add_f32_e32 v116, v127, v116
	v_add_f32_e32 v116, v128, v116
	v_add_f32_e32 v120, v129, v116
	v_cvt_pk_bf16_f32 v156, v124, v125
	v_cvt_pk_bf16_f32 v157, v126, v127
	s_waitcnt lgkmcnt(11)
	v_mfma_f32_32x32x16_bf16 v[100:115], v[164:167], v[144:147], v[100:115]
	ds_read_b64_tr_b16 v[116:117], v2 offset:29696
	ds_read_b64_tr_b16 v[118:119], v2 offset:30208
	v_add_f32_e32 v120, v130, v120
	v_add_f32_e32 v120, v131, v120
	v_add_f32_e32 v120, v52, v120
	v_add_f32_e32 v124, v53, v120
	v_cvt_pk_bf16_f32 v158, v128, v129
	v_cvt_pk_bf16_f32 v159, v130, v131
	s_waitcnt lgkmcnt(12)
	v_mfma_f32_32x32x16_bf16 v[68:83], v[168:171], v[144:147], v[68:83]
	ds_read_b64_tr_b16 v[120:121], v2 offset:26624
	ds_read_b64_tr_b16 v[122:123], v2 offset:27136
	v_add_f32_e32 v124, v54, v124
	v_add_f32_e32 v124, v55, v124
	v_add_f32_e32 v124, v56, v124
	v_add_f32_e32 v124, v57, v124
	v_cvt_pk_bf16_f32 v148, v52, v53
	v_cvt_pk_bf16_f32 v149, v54, v55
	s_waitcnt lgkmcnt(13)
	v_mfma_f32_32x32x16_bf16 v[100:115], v[172:175], v[136:139], v[100:115]
	ds_read_b64_tr_b16 v[52:53], v2 offset:30720
	ds_read_b64_tr_b16 v[54:55], v2 offset:31232
	v_add_f32_e32 v124, v58, v124
	v_add_f32_e32 v124, v59, v124
	v_add_f32_e32 v124, v60, v124
	v_add_f32_e32 v124, v61, v124
	v_cvt_pk_bf16_f32 v150, v56, v57
	v_cvt_pk_bf16_f32 v151, v58, v59
	s_waitcnt lgkmcnt(14)
	v_mfma_f32_32x32x16_bf16 v[68:83], v[176:179], v[136:139], v[68:83]
	ds_read_b64_tr_b16 v[56:57], v2 offset:27648
	ds_read_b64_tr_b16 v[58:59], v2 offset:28160
	v_add_f32_e32 v124, v62, v124
	v_add_f32_e32 v124, v63, v124
	v_add_f32_e32 v124, v64, v124
	v_add_f32_e32 v124, v65, v124
	v_cvt_pk_bf16_f32 v140, v60, v61
	v_cvt_pk_bf16_f32 v141, v62, v63
	s_waitcnt lgkmcnt(14)
	v_mfma_f32_32x32x16_bf16 v[100:115], v[198:201], v[132:135], v[100:115]
	ds_read_b64_tr_b16 v[60:61], v2 offset:31744
	ds_read_b64_tr_b16 v[62:63], v2 offset:32256
	v_mfma_f32_32x32x16_bf16 v[68:83], v[84:87], v[132:135], v[68:83]
	v_add_f32_e32 v84, v66, v124
	v_add_f32_e32 v84, v67, v84
	v_add_f32_e32 v84, 0, v84
	v_cvt_pk_bf16_f32 v142, v64, v65
	v_cvt_pk_bf16_f32 v143, v66, v67
	s_mov_b32 s14, s20
	v_lshl_add_u64 v[64:65], v[180:181], 0, s[20:21]
	s_add_i32 s13, s13, 0xa000
	s_mov_b32 s9, m0
	s_mov_b32 m0, s13
	s_nop 0
	global_load_lds_dwordx4 v[64:65], off
	s_mov_b32 m0, s9
	v_writelane_b32 v254, s14, 56
	v_add_f32_e32 v182, v191, v84
	s_nop 0
	v_writelane_b32 v254, s15, 57
	s_waitcnt lgkmcnt(14)
	v_mfma_f32_32x32x16_bf16 v[4:19], v[160:163], v[88:91], v[4:19]
	v_exp_f32_e32 v100, v100
	v_exp_f32_e32 v101, v101
	v_exp_f32_e32 v102, v102
	v_exp_f32_e32 v103, v103
	s_waitcnt lgkmcnt(12)
	v_mfma_f32_32x32x16_bf16 v[20:35], v[160:163], v[92:95], v[20:35]
	v_exp_f32_e32 v104, v104
	v_exp_f32_e32 v105, v105
	v_exp_f32_e32 v106, v106
	v_exp_f32_e32 v107, v107
	ds_read_b128 v[64:67], v189 offset:16384
	ds_read_b128 v[124:127], v189 offset:16896
	s_waitcnt lgkmcnt(12)
	v_mfma_f32_32x32x16_bf16 v[4:19], v[156:159], v[96:99], v[4:19]
	v_exp_f32_e32 v108, v108
	v_exp_f32_e32 v109, v109
	v_exp_f32_e32 v110, v110
	v_exp_f32_e32 v111, v111
	ds_read_b128 v[128:131], v189 offset:18432
	ds_read_b128 v[164:167], v189 offset:18944
	s_waitcnt lgkmcnt(12)
	v_mfma_f32_32x32x16_bf16 v[20:35], v[156:159], v[116:119], v[20:35]
	v_exp_f32_e32 v112, v112
	v_exp_f32_e32 v113, v113
	v_exp_f32_e32 v114, v114
	v_exp_f32_e32 v115, v115
	ds_read_b128 v[168:171], v189 offset:20480
	ds_read_b128 v[172:175], v189 offset:20992
	s_waitcnt lgkmcnt(12)
	v_mfma_f32_32x32x16_bf16 v[4:19], v[148:151], v[120:123], v[4:19]
	v_exp_f32_e32 v68, v68
	v_exp_f32_e32 v69, v69
	v_exp_f32_e32 v70, v70
	v_exp_f32_e32 v71, v71
	ds_read_b128 v[120:123], v189 offset:22528
	ds_read_b128 v[116:119], v189 offset:23040
	s_waitcnt lgkmcnt(12)
	v_mfma_f32_32x32x16_bf16 v[20:35], v[148:151], v[52:55], v[20:35]
	v_exp_f32_e32 v72, v72
	v_exp_f32_e32 v73, v73
	v_exp_f32_e32 v74, v74
	v_exp_f32_e32 v75, v75
	s_waitcnt lgkmcnt(10)
	v_mfma_f32_32x32x16_bf16 v[4:19], v[140:143], v[56:59], v[4:19]
	v_exp_f32_e32 v76, v76
	v_exp_f32_e32 v77, v77
	v_exp_f32_e32 v78, v78
	v_exp_f32_e32 v79, v79
	s_waitcnt lgkmcnt(8)
	v_mfma_f32_32x32x16_bf16 v[20:35], v[140:143], v[60:63], v[20:35]
	v_exp_f32_e32 v80, v80
	v_exp_f32_e32 v81, v81
	v_exp_f32_e32 v82, v82
	v_exp_f32_e32 v83, v83
	s_waitcnt vmcnt(1) lgkmcnt(0)
	s_barrier
;   #define RESC() do{ if(resc){ asm volatile("s_waitcnt lgkmcnt(0)":::"memory"); \
;       _Pragma("unroll") for(int d_=0;d_<2;++d_) _Pragma("unroll") for(int r=0;r<16;++r)o[d_][r]*=wsf[crow(r,hi)]; } }while(0)
;   #define ROT() do{sl_prev=sl_cur;sl_cur=sl_next;sl_next=(sl_next==(NSLOT-1)*SLOTB)?0:sl_next+SLOTB;}while(0)
;   #define ENDW(tt) do{ if((tt)+3<NT){WAIT_BAR(2);} else if((tt)+2<NT){WAIT_BAR(1);} else {WAIT_BAR(0);} }while(0)
; template<int THRL,bool NOMAX> __device__ __forceinline__ void attn_unit(int b,int h,int qb,int t0,const bf16*Q,const bf16*__restrict__ KV,const bf16*__restrict__ GA,bf16*O,char*shm){
;     ...
;   for(;t+1<NT;t+=2){
;     STEP(pB0,pB1,pA0,pA1,t,(t+3<NT),(t+1<NT),(t+1<NT));       ENDW(t);   RESC(); ROT();
;     STEP(pA0,pA1,pB0,pB1,t+1,(t+4<NT),(t+2<NT),(t+2<NT));     ENDW(t+1); RESC(); ROT();
	ds_read_b64_tr_b16 v[176:177], v2 offset:32768
	ds_read_b64_tr_b16 v[178:179], v2 offset:33280
	v_add_f32_e32 v52, v100, v101
	v_add_f32_e32 v52, v102, v52
	v_add_f32_e32 v52, v103, v52
	v_add_f32_e32 v52, v104, v52
	v_add_f32_e32 v52, v105, v52
	v_cvt_pk_bf16_f32 v160, v100, v101
	v_cvt_pk_bf16_f32 v161, v102, v103
	s_waitcnt lgkmcnt(9)
	v_mfma_f32_32x32x16_bf16 v[84:99], v[64:67], v[152:155], v[36:51]
	ds_read_b64_tr_b16 v[100:101], v2 offset:36864
	ds_read_b64_tr_b16 v[102:103], v2 offset:37376
	v_add_f32_e32 v52, v106, v52
	v_add_f32_e32 v52, v107, v52
	v_add_f32_e32 v52, v108, v52
	v_add_f32_e32 v140, v109, v52
	v_cvt_pk_bf16_f32 v162, v104, v105
	v_cvt_pk_bf16_f32 v163, v106, v107
	s_waitcnt lgkmcnt(10)
	v_mfma_f32_32x32x16_bf16 v[52:67], v[124:127], v[152:155], v[36:51]
	ds_read_b64_tr_b16 v[124:125], v2 offset:33792
	ds_read_b64_tr_b16 v[126:127], v2 offset:34304
	v_add_f32_e32 v104, v110, v140
	v_add_f32_e32 v104, v111, v104
	v_add_f32_e32 v104, v112, v104
	v_add_f32_e32 v104, v113, v104
	v_cvt_pk_bf16_f32 v156, v108, v109
	v_cvt_pk_bf16_f32 v157, v110, v111
	s_waitcnt lgkmcnt(11)
	v_mfma_f32_32x32x16_bf16 v[84:99], v[128:131], v[144:147], v[84:99]
	ds_read_b64_tr_b16 v[106:107], v2 offset:37888
	ds_read_b64_tr_b16 v[108:109], v2 offset:38400
	v_add_f32_e32 v104, v114, v104
	v_add_f32_e32 v104, v115, v104
	v_add_f32_e32 v104, v68, v104
	v_add_f32_e32 v104, v69, v104
	v_cvt_pk_bf16_f32 v158, v112, v113
	v_cvt_pk_bf16_f32 v159, v114, v115
	s_waitcnt lgkmcnt(12)
	v_mfma_f32_32x32x16_bf16 v[52:67], v[164:167], v[144:147], v[52:67]
	ds_read_b64_tr_b16 v[110:111], v2 offset:34816
	ds_read_b64_tr_b16 v[112:113], v2 offset:35328
	v_add_f32_e32 v104, v70, v104
	v_add_f32_e32 v104, v71, v104
	v_add_f32_e32 v104, v72, v104
	v_add_f32_e32 v104, v73, v104
	v_cvt_pk_bf16_f32 v148, v68, v69
	v_cvt_pk_bf16_f32 v149, v70, v71
	s_waitcnt lgkmcnt(13)
	v_mfma_f32_32x32x16_bf16 v[84:99], v[168:171], v[136:139], v[84:99]
	ds_read_b64_tr_b16 v[68:69], v2 offset:38912
	ds_read_b64_tr_b16 v[70:71], v2 offset:39424
	v_add_f32_e32 v104, v74, v104
	v_add_f32_e32 v104, v75, v104
	v_add_f32_e32 v104, v76, v104
	v_add_f32_e32 v104, v77, v104
	v_cvt_pk_bf16_f32 v150, v72, v73
	v_cvt_pk_bf16_f32 v151, v74, v75
	s_waitcnt lgkmcnt(14)
	v_mfma_f32_32x32x16_bf16 v[52:67], v[172:175], v[136:139], v[52:67]
	ds_read_b64_tr_b16 v[72:73], v2 offset:35840
	ds_read_b64_tr_b16 v[74:75], v2 offset:36352
	v_add_f32_e32 v104, v78, v104
	v_add_f32_e32 v104, v79, v104
	v_add_f32_e32 v104, v80, v104
	v_add_f32_e32 v104, v81, v104
	v_cvt_pk_bf16_f32 v140, v76, v77
	v_cvt_pk_bf16_f32 v141, v78, v79
	s_waitcnt lgkmcnt(14)
	v_mfma_f32_32x32x16_bf16 v[84:99], v[120:123], v[132:135], v[84:99]
	ds_read_b64_tr_b16 v[76:77], v2 offset:39936
	ds_read_b64_tr_b16 v[78:79], v2 offset:40448
	v_add_f32_e32 v104, v82, v104
	v_add_f32_e32 v104, v83, v104
	v_add_f32_e32 v104, 0, v104
	v_cvt_pk_bf16_f32 v142, v80, v81
	v_cvt_pk_bf16_f32 v143, v82, v83
	v_mfma_f32_32x32x16_bf16 v[52:67], v[116:119], v[132:135], v[52:67]
	s_mov_b32 s14, s22
	v_lshl_add_u64 v[80:81], v[180:181], 0, s[22:23]
	s_mov_b32 s9, m0
	s_mov_b32 m0, s8
	s_nop 0
	global_load_lds_dwordx4 v[80:81], off
	s_mov_b32 m0, s9
	v_writelane_b32 v254, s14, 60
	v_add_f32_e32 v104, v182, v104
	s_nop 0
	v_writelane_b32 v254, s15, 61
	s_waitcnt lgkmcnt(14)
	v_mfma_f32_32x32x16_bf16 v[4:19], v[160:163], v[176:179], v[4:19]
	v_exp_f32_e32 v84, v84
	v_exp_f32_e32 v85, v85
	v_exp_f32_e32 v86, v86
	v_exp_f32_e32 v87, v87
	s_waitcnt lgkmcnt(12)
	v_mfma_f32_32x32x16_bf16 v[20:35], v[160:163], v[100:103], v[20:35]
	v_exp_f32_e32 v88, v88
	v_exp_f32_e32 v89, v89
	v_exp_f32_e32 v90, v90
	v_exp_f32_e32 v91, v91
	ds_read_b128 v[114:117], v189
	ds_read_b128 v[118:121], v189 offset:512
	s_waitcnt lgkmcnt(12)
	v_mfma_f32_32x32x16_bf16 v[4:19], v[156:159], v[124:127], v[4:19]
	v_exp_f32_e32 v92, v92
	v_exp_f32_e32 v93, v93
	v_exp_f32_e32 v94, v94
	v_exp_f32_e32 v95, v95
	ds_read_b128 v[122:125], v189 offset:2048
	ds_read_b128 v[126:129], v189 offset:2560
	s_waitcnt lgkmcnt(12)
	v_mfma_f32_32x32x16_bf16 v[20:35], v[156:159], v[106:109], v[20:35]
	v_exp_f32_e32 v96, v96
	v_exp_f32_e32 v97, v97
	v_exp_f32_e32 v98, v98
	v_exp_f32_e32 v99, v99
	ds_read_b128 v[106:109], v189 offset:4096
	ds_read_b128 v[164:167], v189 offset:4608
	s_waitcnt lgkmcnt(12)
	v_mfma_f32_32x32x16_bf16 v[4:19], v[148:151], v[110:113], v[4:19]
	v_exp_f32_e32 v52, v52
	v_exp_f32_e32 v53, v53
	v_exp_f32_e32 v54, v54
	v_exp_f32_e32 v55, v55
	ds_read_b128 v[110:113], v189 offset:6144
	ds_read_b128 v[100:103], v189 offset:6656
	s_waitcnt lgkmcnt(12)
	v_mfma_f32_32x32x16_bf16 v[20:35], v[148:151], v[68:71], v[20:35]
	v_exp_f32_e32 v56, v56
	v_exp_f32_e32 v57, v57
	v_exp_f32_e32 v58, v58
	v_exp_f32_e32 v59, v59
	s_waitcnt lgkmcnt(10)
	v_mfma_f32_32x32x16_bf16 v[4:19], v[140:143], v[72:75], v[4:19]
	v_exp_f32_e32 v60, v60
	v_exp_f32_e32 v61, v61
	v_exp_f32_e32 v62, v62
	v_exp_f32_e32 v63, v63
	s_waitcnt lgkmcnt(8)
	v_mfma_f32_32x32x16_bf16 v[20:35], v[140:143], v[76:79], v[20:35]
	v_exp_f32_e32 v64, v64
	v_exp_f32_e32 v65, v65
	v_exp_f32_e32 v66, v66
	v_exp_f32_e32 v67, v67
	s_waitcnt vmcnt(0) lgkmcnt(0)
	s_barrier
;   #define RESC() do{ if(resc){ asm volatile("s_waitcnt lgkmcnt(0)":::"memory"); \
;       _Pragma("unroll") for(int d_=0;d_<2;++d_) _Pragma("unroll") for(int r=0;r<16;++r)o[d_][r]*=wsf[crow(r,hi)]; } }while(0)
; template<int THRL,bool NOMAX> __device__ __forceinline__ void attn_unit(int b,int h,int qb,int t0,const bf16*Q,const bf16*__restrict__ KV,const bf16*__restrict__ GA,bf16*O,char*shm){
;     ...
;   STEP(pB0,pB1,pA0,pA1,NT-1,false,false,false); RESC();
	ds_read_b64_tr_b16 v[168:169], v2 offset:40960
	ds_read_b64_tr_b16 v[170:171], v2 offset:41472
	v_add_f32_e32 v68, v84, v85
	v_add_f32_e32 v68, v86, v68
	v_add_f32_e32 v68, v87, v68
	v_add_f32_e32 v68, v88, v68
	v_add_f32_e32 v105, v89, v68
	v_cvt_pk_bf16_f32 v160, v84, v85
	v_cvt_pk_bf16_f32 v161, v86, v87
	s_waitcnt lgkmcnt(9)
	v_mfma_f32_32x32x16_bf16 v[68:83], v[114:117], v[152:155], v[36:51]
	ds_read_b64_tr_b16 v[84:85], v2 offset:45056
	ds_read_b64_tr_b16 v[86:87], v2 offset:45568
	s_waitcnt lgkmcnt(10)
	v_mfma_f32_32x32x16_bf16 v[36:51], v[118:121], v[152:155], v[36:51]
	v_add_f32_e32 v105, v90, v105
	v_add_f32_e32 v105, v91, v105
	v_add_f32_e32 v105, v92, v105
	v_add_f32_e32 v105, v93, v105
	v_cvt_pk_bf16_f32 v162, v88, v89
	v_cvt_pk_bf16_f32 v163, v90, v91
	ds_read_b64_tr_b16 v[88:89], v2 offset:41984
	ds_read_b64_tr_b16 v[90:91], v2 offset:42496
	v_add_f32_e32 v105, v94, v105
	v_add_f32_e32 v105, v95, v105
	v_add_f32_e32 v105, v96, v105
	v_add_f32_e32 v105, v97, v105
	v_cvt_pk_bf16_f32 v156, v92, v93
	v_cvt_pk_bf16_f32 v157, v94, v95
	s_waitcnt lgkmcnt(11)
	v_mfma_f32_32x32x16_bf16 v[68:83], v[122:125], v[144:147], v[68:83]
	ds_read_b64_tr_b16 v[92:93], v2 offset:46080
	ds_read_b64_tr_b16 v[94:95], v2 offset:46592
	s_waitcnt lgkmcnt(12)
	v_mfma_f32_32x32x16_bf16 v[36:51], v[126:129], v[144:147], v[36:51]
	v_add_f32_e32 v105, v98, v105
	v_add_f32_e32 v105, v99, v105
	v_add_f32_e32 v105, v52, v105
	v_add_f32_e32 v105, v53, v105
	v_cvt_pk_bf16_f32 v158, v96, v97
	v_cvt_pk_bf16_f32 v159, v98, v99
	ds_read_b64_tr_b16 v[96:97], v2 offset:43008
	ds_read_b64_tr_b16 v[98:99], v2 offset:43520
	v_add_f32_e32 v105, v54, v105
	v_add_f32_e32 v105, v55, v105
	v_add_f32_e32 v105, v56, v105
	v_add_f32_e32 v105, v57, v105
	v_cvt_pk_bf16_f32 v148, v52, v53
	v_cvt_pk_bf16_f32 v149, v54, v55
	s_waitcnt lgkmcnt(13)
	v_mfma_f32_32x32x16_bf16 v[68:83], v[106:109], v[136:139], v[68:83]
	ds_read_b64_tr_b16 v[52:53], v2 offset:47104
	ds_read_b64_tr_b16 v[54:55], v2 offset:47616
	s_waitcnt lgkmcnt(14)
	v_mfma_f32_32x32x16_bf16 v[36:51], v[164:167], v[136:139], v[36:51]
	v_add_f32_e32 v105, v58, v105
	v_add_f32_e32 v105, v59, v105
	v_add_f32_e32 v105, v60, v105
	v_add_f32_e32 v105, v61, v105
	v_cvt_pk_bf16_f32 v150, v56, v57
	v_cvt_pk_bf16_f32 v151, v58, v59
	ds_read_b64_tr_b16 v[56:57], v2 offset:44032
	ds_read_b64_tr_b16 v[58:59], v2 offset:44544
	v_add_f32_e32 v105, v62, v105
	v_add_f32_e32 v105, v63, v105
	v_add_f32_e32 v105, v64, v105
	v_add_f32_e32 v105, v65, v105
	v_cvt_pk_bf16_f32 v140, v60, v61
	v_cvt_pk_bf16_f32 v141, v62, v63
	s_waitcnt lgkmcnt(14)
	v_mfma_f32_32x32x16_bf16 v[68:83], v[110:113], v[132:135], v[68:83]
	ds_read_b64_tr_b16 v[60:61], v2 offset:48128
	ds_read_b64_tr_b16 v[62:63], v2 offset:48640
	v_mfma_f32_32x32x16_bf16 v[36:51], v[100:103], v[132:135], v[36:51]
	v_add_f32_e32 v2, v66, v105
	v_add_f32_e32 v2, v67, v2
	v_add_f32_e32 v2, 0, v2
	v_cvt_pk_bf16_f32 v142, v64, v65
	v_cvt_pk_bf16_f32 v143, v66, v67
	s_waitcnt lgkmcnt(14)
	v_mfma_f32_32x32x16_bf16 v[4:19], v[160:163], v[168:171], v[4:19]
	s_nop 1
	v_exp_f32_e32 v68, v68
	v_exp_f32_e32 v69, v69
	v_exp_f32_e32 v70, v70
	v_exp_f32_e32 v71, v71
	s_waitcnt lgkmcnt(12)
	v_mfma_f32_32x32x16_bf16 v[20:35], v[160:163], v[84:87], v[20:35]
	v_exp_f32_e32 v72, v72
	v_exp_f32_e32 v73, v73
	v_exp_f32_e32 v74, v74
	v_exp_f32_e32 v75, v75
	s_waitcnt lgkmcnt(10)
	v_mfma_f32_32x32x16_bf16 v[4:19], v[156:159], v[88:91], v[4:19]
	v_exp_f32_e32 v76, v76
	v_exp_f32_e32 v77, v77
	v_exp_f32_e32 v78, v78
	v_exp_f32_e32 v79, v79
	s_waitcnt lgkmcnt(8)
	v_mfma_f32_32x32x16_bf16 v[20:35], v[156:159], v[92:95], v[20:35]
	v_exp_f32_e32 v80, v80
	v_exp_f32_e32 v81, v81
	v_exp_f32_e32 v82, v82
	v_exp_f32_e32 v83, v83
	s_waitcnt lgkmcnt(6)
; #define SBAR() __builtin_amdgcn_sched_barrier(0)
;   #define RESC() do{ if(resc){ asm volatile("s_waitcnt lgkmcnt(0)":::"memory"); \
;       _Pragma("unroll") for(int d_=0;d_<2;++d_) _Pragma("unroll") for(int r=0;r<16;++r)o[d_][r]*=wsf[crow(r,hi)]; } }while(0)
;   #define PKW(P,B) cvtpk_s(P[B],P[B+1])
; __device__ __forceinline__ void pv(f32x16*o,int vb,bf16x8 pa0,bf16x8 pa1,bf16x8 pa2,bf16x8 pa3){
;   #pragma unroll
;   for(int d0=0;d0<2;++d0){s16x4 lo[4],hi[4];
;     #pragma unroll
;     for(int ks=0;ks<4;++ks){
;       asm volatile("ds_read_b64_tr_b16 %0,%1 offset:%c2":"=&v"(lo[ks]):"v"(vb),"i"(d0*4096+ks*1024):"memory");
;       asm volatile("ds_read_b64_tr_b16 %0,%1 offset:%c2":"=&v"(hi[ks]):"v"(vb),"i"(d0*4096+ks*1024+512):"memory");}
;     asm volatile("s_waitcnt lgkmcnt(0)":::"memory");SBAR();
;     ...
;     o[d0]=__builtin_amdgcn_mfma_f32_32x32x16_bf16(pa0,PK(0),o[d0],0,0,0);
;     o[d0]=__builtin_amdgcn_mfma_f32_32x32x16_bf16(pa1,PK(1),o[d0],0,0,0);
;     o[d0]=__builtin_amdgcn_mfma_f32_32x32x16_bf16(pa2,PK(2),o[d0],0,0,0);
;     o[d0]=__builtin_amdgcn_mfma_f32_32x32x16_bf16(pa3,PK(3),o[d0],0,0,0);
;     ...
;   }
; }
; template<int THRL,bool NOMAX> __device__ __forceinline__ void attn_unit(int b,int h,int qb,int t0,const bf16*Q,const bf16*__restrict__ KV,const bf16*__restrict__ GA,bf16*O,char*shm){
;     ...
;   STEP(pB0,pB1,pA0,pA1,NT-1,false,false,false); RESC();
;   { float sacc=pB0[0]+pB0[1]; _Pragma("unroll") for(int r=2;r<16;++r)sacc+=pB0[r]; _Pragma("unroll") for(int r=0;r<16;++r)sacc+=pB1[r]; l_reg+=sacc;
;     pw0=(u32x4){PKW(pB0,0),PKW(pB0,2),PKW(pB0,4),PKW(pB0,6)};pw1=(u32x4){PKW(pB0,8),PKW(pB0,10),PKW(pB0,12),PKW(pB0,14)};pw2=(u32x4){PKW(pB1,0),PKW(pB1,2),PKW(pB1,4),PKW(pB1,6)};pw3=(u32x4){PKW(pB1,8),PKW(pB1,10),PKW(pB1,12),PKW(pB1,14)};
;     SBAR(); pv(o,vb0+sl_cur,PAF(0),PAF(1),PAF(2),PAF(3)); }
;     ...
;   {auto rr=__builtin_amdgcn_permlane32_swap(__float_as_uint(l_reg),__float_as_uint(l_reg),false,false);l_reg=__uint_as_float(rr[0])+__uint_as_float(rr[1]);}
;   if(hi==0)wsf[32+r32]=l_reg;asm volatile("s_waitcnt lgkmcnt(0)":::"memory");
	v_mfma_f32_32x32x16_bf16 v[4:19], v[148:151], v[96:99], v[4:19]
	v_exp_f32_e32 v36, v36
	v_exp_f32_e32 v37, v37
	v_exp_f32_e32 v38, v38
	v_exp_f32_e32 v39, v39
	s_waitcnt lgkmcnt(4)
	v_mfma_f32_32x32x16_bf16 v[20:35], v[148:151], v[52:55], v[20:35]
	v_exp_f32_e32 v40, v40
	v_exp_f32_e32 v41, v41
	v_exp_f32_e32 v42, v42
	v_exp_f32_e32 v43, v43
	s_waitcnt lgkmcnt(2)
	v_mfma_f32_32x32x16_bf16 v[4:19], v[140:143], v[56:59], v[4:19]
	v_exp_f32_e32 v44, v44
	v_exp_f32_e32 v45, v45
	v_exp_f32_e32 v46, v46
	v_exp_f32_e32 v47, v47
	s_waitcnt lgkmcnt(0)
	v_mfma_f32_32x32x16_bf16 v[20:35], v[140:143], v[60:63], v[20:35]
	v_exp_f32_e32 v48, v48
	v_exp_f32_e32 v49, v49
	v_exp_f32_e32 v50, v50
	v_exp_f32_e32 v51, v51
	v_add_f32_e32 v52, v68, v69
	v_add_f32_e32 v52, v70, v52
	v_add_f32_e32 v52, v71, v52
	v_add_f32_e32 v52, v72, v52
	v_add_f32_e32 v52, v73, v52
	v_add_f32_e32 v52, v74, v52
	v_add_f32_e32 v52, v75, v52
	v_add_f32_e32 v52, v76, v52
	v_add_f32_e32 v52, v77, v52
	v_add_f32_e32 v52, v78, v52
	v_add_f32_e32 v52, v79, v52
	v_add_f32_e32 v52, v80, v52
	v_add_f32_e32 v52, v81, v52
	v_add_f32_e32 v52, v82, v52
	v_add_f32_e32 v52, v83, v52
	v_add_f32_e32 v52, v36, v52
	v_add_f32_e32 v52, v37, v52
	v_add_f32_e32 v52, v38, v52
	v_add_f32_e32 v52, v39, v52
	v_add_f32_e32 v52, v40, v52
	v_add_f32_e32 v52, v41, v52
	v_add_f32_e32 v52, v42, v52
	v_add_f32_e32 v52, v43, v52
	v_add_f32_e32 v52, v44, v52
	v_add_f32_e32 v52, v45, v52
	v_add_f32_e32 v52, v46, v52
	v_add_f32_e32 v52, v47, v52
	v_add_f32_e32 v52, v48, v52
	v_add_f32_e32 v52, v49, v52
	v_add_f32_e32 v52, v50, v52
	v_add_f32_e32 v52, v51, v52
	v_add_f32_e32 v2, v104, v2
	v_add_f32_e32 v2, v2, v52
	v_cvt_pk_bf16_f32 v36, v36, v37
	v_cvt_pk_bf16_f32 v52, v68, v69
	v_cvt_pk_bf16_f32 v53, v70, v71
	v_cvt_pk_bf16_f32 v54, v72, v73
	v_cvt_pk_bf16_f32 v55, v74, v75
	v_cvt_pk_bf16_f32 v56, v76, v77
	v_cvt_pk_bf16_f32 v57, v78, v79
	v_cvt_pk_bf16_f32 v58, v80, v81
	v_cvt_pk_bf16_f32 v59, v82, v83
	v_cvt_pk_bf16_f32 v37, v38, v39
	v_cvt_pk_bf16_f32 v38, v40, v41
	v_cvt_pk_bf16_f32 v39, v42, v43
	v_cvt_pk_bf16_f32 v40, v44, v45
	v_cvt_pk_bf16_f32 v41, v46, v47
	v_cvt_pk_bf16_f32 v42, v48, v49
	v_cvt_pk_bf16_f32 v43, v50, v51
	ds_read_b64_tr_b16 v[44:45],v190 offset:0
	ds_read_b64_tr_b16 v[46:47],v190 offset:512
	ds_read_b64_tr_b16 v[48:49],v190 offset:1024
	ds_read_b64_tr_b16 v[50:51],v190 offset:1536
	ds_read_b64_tr_b16 v[60:61],v190 offset:2048
	ds_read_b64_tr_b16 v[62:63],v190 offset:2560
	ds_read_b64_tr_b16 v[64:65],v190 offset:3072
	ds_read_b64_tr_b16 v[66:67],v190 offset:3584
	s_waitcnt lgkmcnt(0)
	s_nop 0
	v_mfma_f32_32x32x16_bf16 v[4:19], v[52:55], v[44:47], v[4:19]
	ds_read_b64_tr_b16 v[44:45],v190 offset:4096
	ds_read_b64_tr_b16 v[46:47],v190 offset:4608
	v_mfma_f32_32x32x16_bf16 v[4:19], v[56:59], v[48:51], v[4:19]
	ds_read_b64_tr_b16 v[48:49],v190 offset:5120
	ds_read_b64_tr_b16 v[50:51],v190 offset:5632
	v_mfma_f32_32x32x16_bf16 v[4:19], v[36:39], v[60:63], v[4:19]
	ds_read_b64_tr_b16 v[60:61],v190 offset:6144
	ds_read_b64_tr_b16 v[62:63],v190 offset:6656
	v_mfma_f32_32x32x16_bf16 v[4:19], v[40:43], v[64:67], v[4:19]
	ds_read_b64_tr_b16 v[64:65],v190 offset:7168
	ds_read_b64_tr_b16 v[66:67],v190 offset:7680
	s_waitcnt lgkmcnt(0)
	v_mfma_f32_32x32x16_bf16 v[20:35], v[52:55], v[44:47], v[20:35]
	v_cmp_gt_u32_e32 vcc, 32, v184
	v_mfma_f32_32x32x16_bf16 v[20:35], v[56:59], v[48:51], v[20:35]
	v_mfma_f32_32x32x16_bf16 v[20:35], v[36:39], v[60:63], v[20:35]
	v_mov_b32_e32 v36, v2
	s_nop 1
	v_permlane32_swap_b32_e32 v2, v36
	v_mfma_f32_32x32x16_bf16 v[20:35], v[40:43], v[64:67], v[20:35]
	s_and_saveexec_b64 s[8:9], vcc
	s_cbranch_execz .LBB0_470
	v_lshl_add_u32 v37, v185, 2, s12
	v_add_f32_e32 v2, v2, v36
	ds_write_b32 v37, v2 offset:49280
	s_branch .LBB0_470
